# P1 epilogue: per-block vmcnt(0) after the first rotary block removed, unit-header vmcnt(0) removed
# speedup vs baseline: 1.0050x; 1.0037x over previous
.LBB0_175:
	s_mov_b32 s28, s29
	s_ashr_i32 s29, s29, 31
	s_lshl_b64 s[34:35], s[28:29], 20
	s_add_u32 s34, s90, s34
	s_addc_u32 s35, s91, s35
	s_and_b64 s[36:37], s[30:31], exec
	s_mov_b32 s26, s27
	s_cselect_b32 s2, s35, s43
	s_cselect_b32 s29, s34, s42
	s_ashr_i32 s27, s27, 31
	s_lshl_b64 s[36:37], s[26:27], 20
	s_add_u32 s36, s92, s36
	s_addc_u32 s37, s93, s37
	s_and_b64 s[44:45], s[30:31], exec
	s_cselect_b32 s27, s37, s41
	s_cselect_b32 s39, s36, s40
	s_add_u32 s46, s40, 0x100
	s_addc_u32 s47, s41, 0
	s_add_u32 s40, s42, 0x80080
	v_mov_b32_e32 v2, 0
	s_addc_u32 s41, s43, 0
	s_mov_b32 s52, -2
	v_mov_b32_e32 v3, v2
	v_mov_b64_e32 v[4:5], v[2:3]
	v_mov_b64_e32 v[6:7], v[2:3]
	v_mov_b64_e32 v[8:9], v[2:3]
	v_mov_b64_e32 v[18:19], v[2:3]
	v_mov_b64_e32 v[20:21], v[2:3]
	v_mov_b64_e32 v[22:23], v[2:3]
	v_mov_b64_e32 v[24:25], v[2:3]
	v_mov_b64_e32 v[34:35], v[2:3]
	v_mov_b64_e32 v[36:37], v[2:3]
	v_mov_b64_e32 v[38:39], v[2:3]
	v_mov_b64_e32 v[40:41], v[2:3]
	v_mov_b64_e32 v[50:51], v[2:3]
	v_mov_b64_e32 v[52:53], v[2:3]
	v_mov_b64_e32 v[54:55], v[2:3]
	v_mov_b64_e32 v[56:57], v[2:3]
	v_mov_b64_e32 v[10:11], v[2:3]
	v_mov_b64_e32 v[12:13], v[2:3]
	v_mov_b64_e32 v[14:15], v[2:3]
	v_mov_b64_e32 v[16:17], v[2:3]
	v_mov_b64_e32 v[26:27], v[2:3]
	v_mov_b64_e32 v[28:29], v[2:3]
	v_mov_b64_e32 v[30:31], v[2:3]
	v_mov_b64_e32 v[32:33], v[2:3]
	v_mov_b64_e32 v[42:43], v[2:3]
	v_mov_b64_e32 v[44:45], v[2:3]
	v_mov_b64_e32 v[46:47], v[2:3]
	v_mov_b64_e32 v[48:49], v[2:3]
	v_mov_b64_e32 v[66:67], v[2:3]
	v_mov_b64_e32 v[68:69], v[2:3]
	v_mov_b64_e32 v[70:71], v[2:3]
	v_mov_b64_e32 v[72:73], v[2:3]
	v_mov_b64_e32 v[74:75], v[2:3]
	v_mov_b64_e32 v[76:77], v[2:3]
	v_mov_b64_e32 v[86:87], v[2:3]
	v_mov_b64_e32 v[88:89], v[2:3]
	v_mov_b64_e32 v[98:99], v[2:3]
	v_mov_b64_e32 v[100:101], v[2:3]
	v_mov_b64_e32 v[110:111], v[2:3]
	v_mov_b64_e32 v[112:113], v[2:3]
	v_mov_b64_e32 v[130:131], v[2:3]
	v_mov_b64_e32 v[132:133], v[2:3]
	v_mov_b64_e32 v[134:135], v[2:3]
	v_mov_b64_e32 v[136:137], v[2:3]
	v_mov_b64_e32 v[154:155], v[2:3]
	v_mov_b64_e32 v[156:157], v[2:3]
	v_mov_b64_e32 v[158:159], v[2:3]
	v_mov_b64_e32 v[160:161], v[2:3]
	v_mov_b64_e32 v[90:91], v[2:3]
	v_mov_b64_e32 v[92:93], v[2:3]
	v_mov_b64_e32 v[94:95], v[2:3]
	v_mov_b64_e32 v[96:97], v[2:3]
	v_mov_b64_e32 v[114:115], v[2:3]
	v_mov_b64_e32 v[116:117], v[2:3]
	v_mov_b64_e32 v[118:119], v[2:3]
	v_mov_b64_e32 v[120:121], v[2:3]
	v_mov_b64_e32 v[138:139], v[2:3]
	v_mov_b64_e32 v[140:141], v[2:3]
	v_mov_b64_e32 v[142:143], v[2:3]
	v_mov_b64_e32 v[144:145], v[2:3]
	v_mov_b64_e32 v[162:163], v[2:3]
	v_mov_b64_e32 v[164:165], v[2:3]
	v_mov_b64_e32 v[166:167], v[2:3]
	v_mov_b64_e32 v[168:169], v[2:3]
	v_add_u32_e32 v212, 0x18000, v218
	v_add_u32_e32 v213, 0x1c000, v218

; __device__ __forceinline__ unsigned cvt_pk_bf16(float lo, float hi) { unsigned r; asm volatile("v_cvt_pk_bf16_f32 %0, %1, %2" : "=v"(r) : "v"(lo), "v"(hi)); return r; }
;     __device__ __forceinline__ void operator()(const f32x4 (&acc)[2][2][4][2], const Unit& u, int wr, int wc, int fr_, int fq_) const {
;     ...
;                 if (rotl) {
;                     f32x4 w0, w1;
;                     w0[0] = v0[0] * cs0[0] - v0[1] * cs0[1]; w0[1] = v0[1] * cs0[0] + v0[0] * cs0[1];
;                     w0[2] = v0[2] * cs1[0] - v0[3] * cs1[1]; w0[3] = v0[3] * cs1[0] + v0[2] * cs1[1];
;                     w1[0] = v1[0] * cs2[0] - v1[1] * cs2[1]; w1[1] = v1[1] * cs2[0] + v1[0] * cs2[1];
;                     w1[2] = v1[2] * cs3[0] - v1[3] * cs3[1]; w1[3] = v1[3] * cs3[0] + v1[2] * cs3[1];
;                     v0 = w0; v1 = w1;
;                 }
;                 u32x4 w; w.x = cvt_pk_bf16(v0[0], v0[1]); w.y = cvt_pk_bf16(v0[2], v0[3]); w.z = cvt_pk_bf16(v1[0], v1[1]); w.w = cvt_pk_bf16(v1[2], v1[3]);
;                 *(u32x4*)(rowp + bj * hstep) = w;
.LBB0_193:
	s_or_b64 exec, exec, s[44:45]
	v_cvt_pk_bf16_f32 v166, v166, v167
	v_cvt_pk_bf16_f32 v167, v168, v169
	v_cvt_pk_bf16_f32 v168, v162, v163
	v_cvt_pk_bf16_f32 v169, v164, v165
	global_store_dwordx4 v[216:217], v[166:169], off
	s_and_saveexec_b64 s[44:45], s[38:39]
	s_cbranch_execz .LBB0_195
	s_nop 1
	v_pk_mul_f32 v[164:165], v[158:159], v[190:191] op_sel:[1,1] op_sel_hi:[0,1]
	v_pk_mul_f32 v[162:163], v[158:159], v[190:191]
	v_pk_fma_f32 v[158:159], v[158:159], v[190:191], v[164:165] op_sel_hi:[1,0,1]
	v_pk_mul_f32 v[190:191], v[154:155], v[186:187] op_sel:[1,1] op_sel_hi:[0,1]
	v_mul_f32_e32 v158, v161, v193
	v_pk_fma_f32 v[166:167], v[160:161], v[192:193], v[158:159] op_sel_hi:[1,1,0] neg_lo:[0,0,1] neg_hi:[0,0,1]
	v_mul_f32_e32 v158, v160, v193
	v_pk_fma_f32 v[168:169], v[160:161], v[192:193], v[158:159] op_sel:[1,0,0] op_sel_hi:[0,1,0]
	v_pk_mul_f32 v[160:161], v[154:155], v[186:187]
	v_pk_fma_f32 v[154:155], v[154:155], v[186:187], v[190:191] op_sel_hi:[1,0,1]
	v_sub_f32_e32 v158, v162, v164
	v_mul_f32_e32 v154, v157, v189
	v_pk_fma_f32 v[186:187], v[156:157], v[188:189], v[154:155] op_sel_hi:[1,1,0] neg_lo:[0,0,1] neg_hi:[0,0,1]
	v_mul_f32_e32 v154, v156, v189
	v_pk_fma_f32 v[188:189], v[156:157], v[188:189], v[154:155] op_sel:[1,0,0] op_sel_hi:[0,1,0]
	v_sub_f32_e32 v154, v160, v190
	v_mov_b32_e32 v160, v166
	v_mov_b32_e32 v161, v168
	v_mov_b32_e32 v156, v186
	v_mov_b32_e32 v157, v188

; __device__ __forceinline__ unsigned cvt_pk_bf16(float lo, float hi) { unsigned r; asm volatile("v_cvt_pk_bf16_f32 %0, %1, %2" : "=v"(r) : "v"(lo), "v"(hi)); return r; }
;     __device__ __forceinline__ void operator()(const f32x4 (&acc)[2][2][4][2], const Unit& u, int wr, int wc, int fr_, int fq_) const {
;     ...
;             for (int bj = 0; bj < 2; ++bj) {
;                 f32x4 v0 = acc[ai][bj][m][0], v1 = acc[ai][bj][m][1];
;                 if (rotl) {
;                     f32x4 w0, w1;
;                     w0[0] = v0[0] * cs0[0] - v0[1] * cs0[1]; w0[1] = v0[1] * cs0[0] + v0[0] * cs0[1];
;                     w0[2] = v0[2] * cs1[0] - v0[3] * cs1[1]; w0[3] = v0[3] * cs1[0] + v0[2] * cs1[1];
;                     w1[0] = v1[0] * cs2[0] - v1[1] * cs2[1]; w1[1] = v1[1] * cs2[0] + v1[0] * cs2[1];
;                     w1[2] = v1[2] * cs3[0] - v1[3] * cs3[1]; w1[3] = v1[3] * cs3[0] + v1[2] * cs3[1];
;                     v0 = w0; v1 = w1;
;                 }
;                 u32x4 w; w.x = cvt_pk_bf16(v0[0], v0[1]); w.y = cvt_pk_bf16(v0[2], v0[3]); w.z = cvt_pk_bf16(v1[0], v1[1]); w.w = cvt_pk_bf16(v1[2], v1[3]);
;                 *(u32x4*)(rowp + bj * hstep) = w;
.LBB0_200:
	s_nop 1
	v_pk_mul_f32 v[158:159], v[142:143], v[182:183] op_sel:[1,1] op_sel_hi:[0,1]
	v_pk_mul_f32 v[156:157], v[142:143], v[182:183]
	v_pk_fma_f32 v[142:143], v[142:143], v[182:183], v[158:159] op_sel_hi:[1,0,1]
	v_pk_mul_f32 v[164:165], v[138:139], v[178:179] op_sel:[1,1] op_sel_hi:[0,1]
	v_mul_f32_e32 v142, v145, v185
	v_pk_fma_f32 v[160:161], v[144:145], v[184:185], v[142:143] op_sel_hi:[1,1,0] neg_lo:[0,0,1] neg_hi:[0,0,1]
	v_mul_f32_e32 v142, v144, v185
	v_pk_fma_f32 v[162:163], v[144:145], v[184:185], v[142:143] op_sel:[1,0,0] op_sel_hi:[0,1,0]
	v_pk_mul_f32 v[144:145], v[138:139], v[178:179]
	v_pk_fma_f32 v[138:139], v[138:139], v[178:179], v[164:165] op_sel_hi:[1,0,1]
	v_sub_f32_e32 v142, v156, v158
	v_mul_f32_e32 v138, v141, v181
	v_pk_fma_f32 v[166:167], v[140:141], v[180:181], v[138:139] op_sel_hi:[1,1,0] neg_lo:[0,0,1] neg_hi:[0,0,1]
	v_mul_f32_e32 v138, v140, v181
	v_pk_fma_f32 v[168:169], v[140:141], v[180:181], v[138:139] op_sel:[1,0,0] op_sel_hi:[0,1,0]
	v_sub_f32_e32 v138, v144, v164
	v_mov_b32_e32 v144, v160
	v_mov_b32_e32 v145, v162
	v_mov_b32_e32 v140, v166
	v_mov_b32_e32 v141, v168
.LBB0_201:
	s_or_b64 exec, exec, s[44:45]
	v_cvt_pk_bf16_f32 v142, v142, v143
	v_cvt_pk_bf16_f32 v143, v144, v145
	v_cvt_pk_bf16_f32 v144, v138, v139
	v_cvt_pk_bf16_f32 v145, v140, v141
	global_store_dwordx4 v[154:155], v[142:145], off
	s_and_saveexec_b64 s[44:45], s[38:39]
	s_cbranch_execz .LBB0_203
	s_nop 1
	v_pk_mul_f32 v[140:141], v[134:135], v[182:183] op_sel:[1,1] op_sel_hi:[0,1]
	v_pk_mul_f32 v[138:139], v[134:135], v[182:183]
	v_pk_fma_f32 v[134:135], v[134:135], v[182:183], v[140:141] op_sel_hi:[1,0,1]
	v_pk_mul_f32 v[156:157], v[130:131], v[178:179] op_sel:[1,1] op_sel_hi:[0,1]
	v_mul_f32_e32 v134, v137, v185
	v_pk_fma_f32 v[142:143], v[136:137], v[184:185], v[134:135] op_sel_hi:[1,1,0] neg_lo:[0,0,1] neg_hi:[0,0,1]
	v_mul_f32_e32 v134, v136, v185
	v_pk_fma_f32 v[144:145], v[136:137], v[184:185], v[134:135] op_sel:[1,0,0] op_sel_hi:[0,1,0]
	v_pk_mul_f32 v[136:137], v[130:131], v[178:179]
	v_pk_fma_f32 v[130:131], v[130:131], v[178:179], v[156:157] op_sel_hi:[1,0,1]
	v_sub_f32_e32 v134, v138, v140
	v_mul_f32_e32 v130, v133, v181
	v_pk_fma_f32 v[158:159], v[132:133], v[180:181], v[130:131] op_sel_hi:[1,1,0] neg_lo:[0,0,1] neg_hi:[0,0,1]
	v_mul_f32_e32 v130, v132, v181
	v_pk_fma_f32 v[160:161], v[132:133], v[180:181], v[130:131] op_sel:[1,0,0] op_sel_hi:[0,1,0]
	v_sub_f32_e32 v130, v136, v156
	v_mov_b32_e32 v136, v142
	v_mov_b32_e32 v137, v144
	v_mov_b32_e32 v132, v158
	v_mov_b32_e32 v133, v160

; __device__ __forceinline__ unsigned cvt_pk_bf16(float lo, float hi) { unsigned r; asm volatile("v_cvt_pk_bf16_f32 %0, %1, %2" : "=v"(r) : "v"(lo), "v"(hi)); return r; }
;     __device__ __forceinline__ void operator()(const f32x4 (&acc)[2][2][4][2], const Unit& u, int wr, int wc, int fr_, int fq_) const {
;     ...
;             for (int bj = 0; bj < 2; ++bj) {
;                 f32x4 v0 = acc[ai][bj][m][0], v1 = acc[ai][bj][m][1];
;                 if (rotl) {
;                     f32x4 w0, w1;
;                     w0[0] = v0[0] * cs0[0] - v0[1] * cs0[1]; w0[1] = v0[1] * cs0[0] + v0[0] * cs0[1];
;                     w0[2] = v0[2] * cs1[0] - v0[3] * cs1[1]; w0[3] = v0[3] * cs1[0] + v0[2] * cs1[1];
;                     w1[0] = v1[0] * cs2[0] - v1[1] * cs2[1]; w1[1] = v1[1] * cs2[0] + v1[0] * cs2[1];
;                     w1[2] = v1[2] * cs3[0] - v1[3] * cs3[1]; w1[3] = v1[3] * cs3[0] + v1[2] * cs3[1];
;                     v0 = w0; v1 = w1;
;                 }
;                 u32x4 w; w.x = cvt_pk_bf16(v0[0], v0[1]); w.y = cvt_pk_bf16(v0[2], v0[3]); w.z = cvt_pk_bf16(v1[0], v1[1]); w.w = cvt_pk_bf16(v1[2], v1[3]);
;                 *(u32x4*)(rowp + bj * hstep) = w;
.LBB0_208:
	s_nop 1
	v_pk_mul_f32 v[134:135], v[118:119], v[174:175] op_sel:[1,1] op_sel_hi:[0,1]
	v_pk_mul_f32 v[132:133], v[118:119], v[174:175]
	v_pk_fma_f32 v[118:119], v[118:119], v[174:175], v[134:135] op_sel_hi:[1,0,1]
	v_pk_mul_f32 v[140:141], v[114:115], v[170:171] op_sel:[1,1] op_sel_hi:[0,1]
	v_mul_f32_e32 v118, v121, v177
	v_pk_fma_f32 v[136:137], v[120:121], v[176:177], v[118:119] op_sel_hi:[1,1,0] neg_lo:[0,0,1] neg_hi:[0,0,1]
	v_mul_f32_e32 v118, v120, v177
	v_pk_fma_f32 v[138:139], v[120:121], v[176:177], v[118:119] op_sel:[1,0,0] op_sel_hi:[0,1,0]
	v_pk_mul_f32 v[120:121], v[114:115], v[170:171]
	v_pk_fma_f32 v[114:115], v[114:115], v[170:171], v[140:141] op_sel_hi:[1,0,1]
	v_sub_f32_e32 v118, v132, v134
	v_mul_f32_e32 v114, v117, v173
	v_pk_fma_f32 v[142:143], v[116:117], v[172:173], v[114:115] op_sel_hi:[1,1,0] neg_lo:[0,0,1] neg_hi:[0,0,1]
	v_mul_f32_e32 v114, v116, v173
	v_pk_fma_f32 v[144:145], v[116:117], v[172:173], v[114:115] op_sel:[1,0,0] op_sel_hi:[0,1,0]
	v_sub_f32_e32 v114, v120, v140
	v_mov_b32_e32 v120, v136
	v_mov_b32_e32 v121, v138
	v_mov_b32_e32 v116, v142
	v_mov_b32_e32 v117, v144
.LBB0_209:
	s_or_b64 exec, exec, s[44:45]
	v_cvt_pk_bf16_f32 v118, v118, v119
	v_cvt_pk_bf16_f32 v119, v120, v121
	v_cvt_pk_bf16_f32 v120, v114, v115
	v_cvt_pk_bf16_f32 v121, v116, v117
	global_store_dwordx4 v[130:131], v[118:121], off
	s_and_saveexec_b64 s[44:45], s[38:39]
	s_cbranch_execz .LBB0_211
	s_nop 1
	v_pk_mul_f32 v[116:117], v[110:111], v[174:175] op_sel:[1,1] op_sel_hi:[0,1]
	v_pk_mul_f32 v[114:115], v[110:111], v[174:175]
	v_pk_fma_f32 v[110:111], v[110:111], v[174:175], v[116:117] op_sel_hi:[1,0,1]
	v_pk_mul_f32 v[132:133], v[98:99], v[170:171] op_sel:[1,1] op_sel_hi:[0,1]
	v_mul_f32_e32 v110, v113, v177
	v_pk_fma_f32 v[118:119], v[112:113], v[176:177], v[110:111] op_sel_hi:[1,1,0] neg_lo:[0,0,1] neg_hi:[0,0,1]
	v_mul_f32_e32 v110, v112, v177
	v_pk_fma_f32 v[120:121], v[112:113], v[176:177], v[110:111] op_sel:[1,0,0] op_sel_hi:[0,1,0]
	v_pk_mul_f32 v[112:113], v[98:99], v[170:171]
	v_pk_fma_f32 v[98:99], v[98:99], v[170:171], v[132:133] op_sel_hi:[1,0,1]
	v_sub_f32_e32 v110, v114, v116
	v_mul_f32_e32 v98, v101, v173
	v_pk_fma_f32 v[134:135], v[100:101], v[172:173], v[98:99] op_sel_hi:[1,1,0] neg_lo:[0,0,1] neg_hi:[0,0,1]
	v_mul_f32_e32 v98, v100, v173
	v_pk_fma_f32 v[136:137], v[100:101], v[172:173], v[98:99] op_sel:[1,0,0] op_sel_hi:[0,1,0]
	v_sub_f32_e32 v98, v112, v132
	v_mov_b32_e32 v112, v118
	v_mov_b32_e32 v113, v120
	v_mov_b32_e32 v100, v134
	v_mov_b32_e32 v101, v136

; __device__ __forceinline__ unsigned cvt_pk_bf16(float lo, float hi) { unsigned r; asm volatile("v_cvt_pk_bf16_f32 %0, %1, %2" : "=v"(r) : "v"(lo), "v"(hi)); return r; }
;     __device__ __forceinline__ void operator()(const f32x4 (&acc)[2][2][4][2], const Unit& u, int wr, int wc, int fr_, int fq_) const {
;     ...
;             for (int bj = 0; bj < 2; ++bj) {
;                 f32x4 v0 = acc[ai][bj][m][0], v1 = acc[ai][bj][m][1];
;                 if (rotl) {
;                     f32x4 w0, w1;
;                     w0[0] = v0[0] * cs0[0] - v0[1] * cs0[1]; w0[1] = v0[1] * cs0[0] + v0[0] * cs0[1];
;                     w0[2] = v0[2] * cs1[0] - v0[3] * cs1[1]; w0[3] = v0[3] * cs1[0] + v0[2] * cs1[1];
;                     w1[0] = v1[0] * cs2[0] - v1[1] * cs2[1]; w1[1] = v1[1] * cs2[0] + v1[0] * cs2[1];
;                     w1[2] = v1[2] * cs3[0] - v1[3] * cs3[1]; w1[3] = v1[3] * cs3[0] + v1[2] * cs3[1];
;                     v0 = w0; v1 = w1;
;                 }
;                 u32x4 w; w.x = cvt_pk_bf16(v0[0], v0[1]); w.y = cvt_pk_bf16(v0[2], v0[3]); w.z = cvt_pk_bf16(v1[0], v1[1]); w.w = cvt_pk_bf16(v1[2], v1[3]);
;                 *(u32x4*)(rowp + bj * hstep) = w;
.LBB0_216:
	s_nop 1
	v_pk_mul_f32 v[110:111], v[94:95], v[150:151] op_sel:[1,1] op_sel_hi:[0,1]
	v_pk_mul_f32 v[100:101], v[94:95], v[150:151]
	v_pk_fma_f32 v[94:95], v[94:95], v[150:151], v[110:111] op_sel_hi:[1,0,1]
	v_pk_mul_f32 v[116:117], v[90:91], v[146:147] op_sel:[1,1] op_sel_hi:[0,1]
	v_mul_f32_e32 v94, v97, v153
	v_pk_fma_f32 v[112:113], v[96:97], v[152:153], v[94:95] op_sel_hi:[1,1,0] neg_lo:[0,0,1] neg_hi:[0,0,1]
	v_mul_f32_e32 v94, v96, v153
	v_pk_fma_f32 v[114:115], v[96:97], v[152:153], v[94:95] op_sel:[1,0,0] op_sel_hi:[0,1,0]
	v_pk_mul_f32 v[96:97], v[90:91], v[146:147]
	v_pk_fma_f32 v[90:91], v[90:91], v[146:147], v[116:117] op_sel_hi:[1,0,1]
	v_sub_f32_e32 v94, v100, v110
	v_mul_f32_e32 v90, v93, v149
	v_pk_fma_f32 v[118:119], v[92:93], v[148:149], v[90:91] op_sel_hi:[1,1,0] neg_lo:[0,0,1] neg_hi:[0,0,1]
	v_mul_f32_e32 v90, v92, v149
	v_pk_fma_f32 v[120:121], v[92:93], v[148:149], v[90:91] op_sel:[1,0,0] op_sel_hi:[0,1,0]
	v_sub_f32_e32 v90, v96, v116
	v_mov_b32_e32 v96, v112
	v_mov_b32_e32 v97, v114
	v_mov_b32_e32 v92, v118
	v_mov_b32_e32 v93, v120
.LBB0_217:
	s_or_b64 exec, exec, s[44:45]
	v_cvt_pk_bf16_f32 v94, v94, v95
	v_cvt_pk_bf16_f32 v95, v96, v97
	v_cvt_pk_bf16_f32 v96, v90, v91
	v_cvt_pk_bf16_f32 v97, v92, v93
	global_store_dwordx4 v[98:99], v[94:97], off
	s_and_saveexec_b64 s[44:45], s[38:39]
	s_cbranch_execz .LBB0_219
	s_nop 1
	v_pk_mul_f32 v[92:93], v[86:87], v[150:151] op_sel:[1,1] op_sel_hi:[0,1]
	v_pk_mul_f32 v[90:91], v[86:87], v[150:151]
	v_pk_fma_f32 v[86:87], v[86:87], v[150:151], v[92:93] op_sel_hi:[1,0,1]
	v_pk_mul_f32 v[100:101], v[74:75], v[146:147] op_sel:[1,1] op_sel_hi:[0,1]
	v_mul_f32_e32 v86, v89, v153
	v_pk_fma_f32 v[94:95], v[88:89], v[152:153], v[86:87] op_sel_hi:[1,1,0] neg_lo:[0,0,1] neg_hi:[0,0,1]
	v_mul_f32_e32 v86, v88, v153
	v_pk_fma_f32 v[96:97], v[88:89], v[152:153], v[86:87] op_sel:[1,0,0] op_sel_hi:[0,1,0]
	v_pk_mul_f32 v[88:89], v[74:75], v[146:147]
	v_pk_fma_f32 v[74:75], v[74:75], v[146:147], v[100:101] op_sel_hi:[1,0,1]
	v_sub_f32_e32 v86, v90, v92
	v_mul_f32_e32 v74, v77, v149
	v_pk_fma_f32 v[110:111], v[76:77], v[148:149], v[74:75] op_sel_hi:[1,1,0] neg_lo:[0,0,1] neg_hi:[0,0,1]
	v_mul_f32_e32 v74, v76, v149
	v_pk_fma_f32 v[112:113], v[76:77], v[148:149], v[74:75] op_sel:[1,0,0] op_sel_hi:[0,1,0]
	v_sub_f32_e32 v74, v88, v100
	v_mov_b32_e32 v88, v94
	v_mov_b32_e32 v89, v96
	v_mov_b32_e32 v76, v110
	v_mov_b32_e32 v77, v112

; __device__ __forceinline__ unsigned cvt_pk_bf16(float lo, float hi) { unsigned r; asm volatile("v_cvt_pk_bf16_f32 %0, %1, %2" : "=v"(r) : "v"(lo), "v"(hi)); return r; }
;     __device__ __forceinline__ void operator()(const f32x4 (&acc)[2][2][4][2], const Unit& u, int wr, int wc, int fr_, int fq_) const {
;     ...
;             for (int bj = 0; bj < 2; ++bj) {
;                 f32x4 v0 = acc[ai][bj][m][0], v1 = acc[ai][bj][m][1];
;                 if (rotl) {
;                     f32x4 w0, w1;
;                     w0[0] = v0[0] * cs0[0] - v0[1] * cs0[1]; w0[1] = v0[1] * cs0[0] + v0[0] * cs0[1];
;                     w0[2] = v0[2] * cs1[0] - v0[3] * cs1[1]; w0[3] = v0[3] * cs1[0] + v0[2] * cs1[1];
;                     w1[0] = v1[0] * cs2[0] - v1[1] * cs2[1]; w1[1] = v1[1] * cs2[0] + v1[0] * cs2[1];
;                     w1[2] = v1[2] * cs3[0] - v1[3] * cs3[1]; w1[3] = v1[3] * cs3[0] + v1[2] * cs3[1];
;                     v0 = w0; v1 = w1;
;                 }
;                 u32x4 w; w.x = cvt_pk_bf16(v0[0], v0[1]); w.y = cvt_pk_bf16(v0[2], v0[3]); w.z = cvt_pk_bf16(v1[0], v1[1]); w.w = cvt_pk_bf16(v1[2], v1[3]);
;                 *(u32x4*)(rowp + bj * hstep) = w;
.LBB0_224:
	s_nop 1
	v_pk_mul_f32 v[86:87], v[70:71], v[126:127] op_sel:[1,1] op_sel_hi:[0,1]
	v_pk_mul_f32 v[76:77], v[70:71], v[126:127]
	v_pk_fma_f32 v[70:71], v[70:71], v[126:127], v[86:87] op_sel_hi:[1,0,1]
	v_pk_mul_f32 v[92:93], v[66:67], v[122:123] op_sel:[1,1] op_sel_hi:[0,1]
	v_mul_f32_e32 v70, v73, v129
	v_pk_fma_f32 v[88:89], v[72:73], v[128:129], v[70:71] op_sel_hi:[1,1,0] neg_lo:[0,0,1] neg_hi:[0,0,1]
	v_mul_f32_e32 v70, v72, v129
	v_pk_fma_f32 v[90:91], v[72:73], v[128:129], v[70:71] op_sel:[1,0,0] op_sel_hi:[0,1,0]
	v_pk_mul_f32 v[72:73], v[66:67], v[122:123]
	v_pk_fma_f32 v[66:67], v[66:67], v[122:123], v[92:93] op_sel_hi:[1,0,1]
	v_sub_f32_e32 v70, v76, v86
	v_mul_f32_e32 v66, v69, v125
	v_pk_fma_f32 v[94:95], v[68:69], v[124:125], v[66:67] op_sel_hi:[1,1,0] neg_lo:[0,0,1] neg_hi:[0,0,1]
	v_mul_f32_e32 v66, v68, v125
	v_pk_fma_f32 v[96:97], v[68:69], v[124:125], v[66:67] op_sel:[1,0,0] op_sel_hi:[0,1,0]
	v_sub_f32_e32 v66, v72, v92
	v_mov_b32_e32 v72, v88
	v_mov_b32_e32 v73, v90
	v_mov_b32_e32 v68, v94
	v_mov_b32_e32 v69, v96
.LBB0_225:
	s_or_b64 exec, exec, s[44:45]
	v_cvt_pk_bf16_f32 v70, v70, v71
	v_cvt_pk_bf16_f32 v71, v72, v73
	v_cvt_pk_bf16_f32 v72, v66, v67
	v_cvt_pk_bf16_f32 v73, v68, v69
	global_store_dwordx4 v[74:75], v[70:73], off
	s_and_saveexec_b64 s[44:45], s[38:39]
	s_cbranch_execz .LBB0_227
	s_nop 1
	v_pk_mul_f32 v[68:69], v[54:55], v[126:127] op_sel:[1,1] op_sel_hi:[0,1]
	v_pk_mul_f32 v[66:67], v[54:55], v[126:127]
	v_pk_fma_f32 v[54:55], v[54:55], v[126:127], v[68:69] op_sel_hi:[1,0,1]
	v_pk_mul_f32 v[76:77], v[50:51], v[122:123] op_sel:[1,1] op_sel_hi:[0,1]
	v_mul_f32_e32 v54, v57, v129
	v_pk_fma_f32 v[70:71], v[56:57], v[128:129], v[54:55] op_sel_hi:[1,1,0] neg_lo:[0,0,1] neg_hi:[0,0,1]
	v_mul_f32_e32 v54, v56, v129
	v_pk_fma_f32 v[72:73], v[56:57], v[128:129], v[54:55] op_sel:[1,0,0] op_sel_hi:[0,1,0]
	v_pk_mul_f32 v[56:57], v[50:51], v[122:123]
	v_pk_fma_f32 v[50:51], v[50:51], v[122:123], v[76:77] op_sel_hi:[1,0,1]
	v_sub_f32_e32 v54, v66, v68
	v_mul_f32_e32 v50, v53, v125
	v_pk_fma_f32 v[86:87], v[52:53], v[124:125], v[50:51] op_sel_hi:[1,1,0] neg_lo:[0,0,1] neg_hi:[0,0,1]
	v_mul_f32_e32 v50, v52, v125
	v_pk_fma_f32 v[88:89], v[52:53], v[124:125], v[50:51] op_sel:[1,0,0] op_sel_hi:[0,1,0]
	v_sub_f32_e32 v50, v56, v76
	v_mov_b32_e32 v56, v70
	v_mov_b32_e32 v57, v72
	v_mov_b32_e32 v52, v86
	v_mov_b32_e32 v53, v88

; __device__ __forceinline__ unsigned cvt_pk_bf16(float lo, float hi) { unsigned r; asm volatile("v_cvt_pk_bf16_f32 %0, %1, %2" : "=v"(r) : "v"(lo), "v"(hi)); return r; }
;     __device__ __forceinline__ void operator()(const f32x4 (&acc)[2][2][4][2], const Unit& u, int wr, int wc, int fr_, int fq_) const {
;     ...
;             for (int bj = 0; bj < 2; ++bj) {
;                 f32x4 v0 = acc[ai][bj][m][0], v1 = acc[ai][bj][m][1];
;                 if (rotl) {
;                     f32x4 w0, w1;
;                     w0[0] = v0[0] * cs0[0] - v0[1] * cs0[1]; w0[1] = v0[1] * cs0[0] + v0[0] * cs0[1];
;                     w0[2] = v0[2] * cs1[0] - v0[3] * cs1[1]; w0[3] = v0[3] * cs1[0] + v0[2] * cs1[1];
;                     w1[0] = v1[0] * cs2[0] - v1[1] * cs2[1]; w1[1] = v1[1] * cs2[0] + v1[0] * cs2[1];
;                     w1[2] = v1[2] * cs3[0] - v1[3] * cs3[1]; w1[3] = v1[3] * cs3[0] + v1[2] * cs3[1];
;                     v0 = w0; v1 = w1;
;                 }
;                 u32x4 w; w.x = cvt_pk_bf16(v0[0], v0[1]); w.y = cvt_pk_bf16(v0[2], v0[3]); w.z = cvt_pk_bf16(v1[0], v1[1]); w.w = cvt_pk_bf16(v1[2], v1[3]);
;                 *(u32x4*)(rowp + bj * hstep) = w;
.LBB0_232:
	s_nop 1
	v_pk_mul_f32 v[54:55], v[46:47], v[106:107] op_sel:[1,1] op_sel_hi:[0,1]
	v_pk_mul_f32 v[52:53], v[46:47], v[106:107]
	v_pk_fma_f32 v[46:47], v[46:47], v[106:107], v[54:55] op_sel_hi:[1,0,1]
	v_pk_mul_f32 v[68:69], v[42:43], v[102:103] op_sel:[1,1] op_sel_hi:[0,1]
	v_mul_f32_e32 v46, v49, v109
	v_pk_fma_f32 v[56:57], v[48:49], v[108:109], v[46:47] op_sel_hi:[1,1,0] neg_lo:[0,0,1] neg_hi:[0,0,1]
	v_mul_f32_e32 v46, v48, v109
	v_pk_fma_f32 v[66:67], v[48:49], v[108:109], v[46:47] op_sel:[1,0,0] op_sel_hi:[0,1,0]
	v_pk_mul_f32 v[48:49], v[42:43], v[102:103]
	v_pk_fma_f32 v[42:43], v[42:43], v[102:103], v[68:69] op_sel_hi:[1,0,1]
	v_sub_f32_e32 v46, v52, v54
	v_mul_f32_e32 v42, v45, v105
	v_pk_fma_f32 v[70:71], v[44:45], v[104:105], v[42:43] op_sel_hi:[1,1,0] neg_lo:[0,0,1] neg_hi:[0,0,1]
	v_mul_f32_e32 v42, v44, v105
	v_pk_fma_f32 v[72:73], v[44:45], v[104:105], v[42:43] op_sel:[1,0,0] op_sel_hi:[0,1,0]
	v_sub_f32_e32 v42, v48, v68
	v_mov_b32_e32 v48, v56
	v_mov_b32_e32 v49, v66
	v_mov_b32_e32 v44, v70
	v_mov_b32_e32 v45, v72
.LBB0_233:
	s_or_b64 exec, exec, s[44:45]
	v_cvt_pk_bf16_f32 v46, v46, v47
	v_cvt_pk_bf16_f32 v47, v48, v49
	v_cvt_pk_bf16_f32 v48, v42, v43
	v_cvt_pk_bf16_f32 v49, v44, v45
	global_store_dwordx4 v[50:51], v[46:49], off
	s_and_saveexec_b64 s[44:45], s[38:39]
	s_cbranch_execz .LBB0_235
	s_nop 1
	v_pk_mul_f32 v[44:45], v[38:39], v[106:107] op_sel:[1,1] op_sel_hi:[0,1]
	v_pk_mul_f32 v[42:43], v[38:39], v[106:107]
	v_pk_fma_f32 v[38:39], v[38:39], v[106:107], v[44:45] op_sel_hi:[1,0,1]
	v_pk_mul_f32 v[52:53], v[34:35], v[102:103] op_sel:[1,1] op_sel_hi:[0,1]
	v_mul_f32_e32 v38, v41, v109
	v_pk_fma_f32 v[46:47], v[40:41], v[108:109], v[38:39] op_sel_hi:[1,1,0] neg_lo:[0,0,1] neg_hi:[0,0,1]
	v_mul_f32_e32 v38, v40, v109
	v_pk_fma_f32 v[48:49], v[40:41], v[108:109], v[38:39] op_sel:[1,0,0] op_sel_hi:[0,1,0]
	v_pk_mul_f32 v[40:41], v[34:35], v[102:103]
	v_pk_fma_f32 v[34:35], v[34:35], v[102:103], v[52:53] op_sel_hi:[1,0,1]
	v_sub_f32_e32 v38, v42, v44
	v_mul_f32_e32 v34, v37, v105
	v_pk_fma_f32 v[54:55], v[36:37], v[104:105], v[34:35] op_sel_hi:[1,1,0] neg_lo:[0,0,1] neg_hi:[0,0,1]
	v_mul_f32_e32 v34, v36, v105
	v_pk_fma_f32 v[56:57], v[36:37], v[104:105], v[34:35] op_sel:[1,0,0] op_sel_hi:[0,1,0]
	v_sub_f32_e32 v34, v40, v52
	v_mov_b32_e32 v40, v46
	v_mov_b32_e32 v41, v48
	v_mov_b32_e32 v36, v54
	v_mov_b32_e32 v37, v56

; __device__ __forceinline__ unsigned cvt_pk_bf16(float lo, float hi) { unsigned r; asm volatile("v_cvt_pk_bf16_f32 %0, %1, %2" : "=v"(r) : "v"(lo), "v"(hi)); return r; }
;     __device__ __forceinline__ void operator()(const f32x4 (&acc)[2][2][4][2], const Unit& u, int wr, int wc, int fr_, int fq_) const {
;     ...
;             for (int bj = 0; bj < 2; ++bj) {
;                 f32x4 v0 = acc[ai][bj][m][0], v1 = acc[ai][bj][m][1];
;                 if (rotl) {
;                     f32x4 w0, w1;
;                     w0[0] = v0[0] * cs0[0] - v0[1] * cs0[1]; w0[1] = v0[1] * cs0[0] + v0[0] * cs0[1];
;                     w0[2] = v0[2] * cs1[0] - v0[3] * cs1[1]; w0[3] = v0[3] * cs1[0] + v0[2] * cs1[1];
;                     w1[0] = v1[0] * cs2[0] - v1[1] * cs2[1]; w1[1] = v1[1] * cs2[0] + v1[0] * cs2[1];
;                     w1[2] = v1[2] * cs3[0] - v1[3] * cs3[1]; w1[3] = v1[3] * cs3[0] + v1[2] * cs3[1];
;                     v0 = w0; v1 = w1;
;                 }
;                 u32x4 w; w.x = cvt_pk_bf16(v0[0], v0[1]); w.y = cvt_pk_bf16(v0[2], v0[3]); w.z = cvt_pk_bf16(v1[0], v1[1]); w.w = cvt_pk_bf16(v1[2], v1[3]);
;                 *(u32x4*)(rowp + bj * hstep) = w;
.LBB0_240:
	s_nop 1
	v_pk_mul_f32 v[38:39], v[30:31], v[82:83] op_sel:[1,1] op_sel_hi:[0,1]
	v_pk_mul_f32 v[36:37], v[30:31], v[82:83]
	v_pk_fma_f32 v[30:31], v[30:31], v[82:83], v[38:39] op_sel_hi:[1,0,1]
	v_pk_mul_f32 v[44:45], v[26:27], v[78:79] op_sel:[1,1] op_sel_hi:[0,1]
	v_mul_f32_e32 v30, v33, v85
	v_pk_fma_f32 v[40:41], v[32:33], v[84:85], v[30:31] op_sel_hi:[1,1,0] neg_lo:[0,0,1] neg_hi:[0,0,1]
	v_mul_f32_e32 v30, v32, v85
	v_pk_fma_f32 v[42:43], v[32:33], v[84:85], v[30:31] op_sel:[1,0,0] op_sel_hi:[0,1,0]
	v_pk_mul_f32 v[32:33], v[26:27], v[78:79]
	v_pk_fma_f32 v[26:27], v[26:27], v[78:79], v[44:45] op_sel_hi:[1,0,1]
	v_sub_f32_e32 v30, v36, v38
	v_mul_f32_e32 v26, v29, v81
	v_pk_fma_f32 v[46:47], v[28:29], v[80:81], v[26:27] op_sel_hi:[1,1,0] neg_lo:[0,0,1] neg_hi:[0,0,1]
	v_mul_f32_e32 v26, v28, v81
	v_pk_fma_f32 v[48:49], v[28:29], v[80:81], v[26:27] op_sel:[1,0,0] op_sel_hi:[0,1,0]
	v_sub_f32_e32 v26, v32, v44
	v_mov_b32_e32 v32, v40
	v_mov_b32_e32 v33, v42
	v_mov_b32_e32 v28, v46
	v_mov_b32_e32 v29, v48
.LBB0_241:
	s_or_b64 exec, exec, s[44:45]
	v_cvt_pk_bf16_f32 v30, v30, v31
	v_cvt_pk_bf16_f32 v31, v32, v33
	v_cvt_pk_bf16_f32 v32, v26, v27
	v_cvt_pk_bf16_f32 v33, v28, v29
	global_store_dwordx4 v[34:35], v[30:33], off
	s_and_saveexec_b64 s[44:45], s[38:39]
	s_cbranch_execz .LBB0_243
	s_nop 1
	v_pk_mul_f32 v[28:29], v[22:23], v[82:83] op_sel:[1,1] op_sel_hi:[0,1]
	v_pk_mul_f32 v[26:27], v[22:23], v[82:83]
	v_pk_fma_f32 v[22:23], v[22:23], v[82:83], v[28:29] op_sel_hi:[1,0,1]
	v_pk_mul_f32 v[36:37], v[18:19], v[78:79] op_sel:[1,1] op_sel_hi:[0,1]
	v_mul_f32_e32 v22, v25, v85
	v_pk_fma_f32 v[30:31], v[24:25], v[84:85], v[22:23] op_sel_hi:[1,1,0] neg_lo:[0,0,1] neg_hi:[0,0,1]
	v_mul_f32_e32 v22, v24, v85
	v_pk_fma_f32 v[32:33], v[24:25], v[84:85], v[22:23] op_sel:[1,0,0] op_sel_hi:[0,1,0]
	v_pk_mul_f32 v[24:25], v[18:19], v[78:79]
	v_pk_fma_f32 v[18:19], v[18:19], v[78:79], v[36:37] op_sel_hi:[1,0,1]
	v_sub_f32_e32 v22, v26, v28
	v_mul_f32_e32 v18, v21, v81
	v_pk_fma_f32 v[38:39], v[20:21], v[80:81], v[18:19] op_sel_hi:[1,1,0] neg_lo:[0,0,1] neg_hi:[0,0,1]
	v_mul_f32_e32 v18, v20, v81
	v_pk_fma_f32 v[40:41], v[20:21], v[80:81], v[18:19] op_sel:[1,0,0] op_sel_hi:[0,1,0]
	v_sub_f32_e32 v18, v24, v36
	v_mov_b32_e32 v24, v30
	v_mov_b32_e32 v25, v32
	v_mov_b32_e32 v20, v38
	v_mov_b32_e32 v21, v40

; __device__ __forceinline__ unsigned cvt_pk_bf16(float lo, float hi) { unsigned r; asm volatile("v_cvt_pk_bf16_f32 %0, %1, %2" : "=v"(r) : "v"(lo), "v"(hi)); return r; }
;     __device__ __forceinline__ void operator()(const f32x4 (&acc)[2][2][4][2], const Unit& u, int wr, int wc, int fr_, int fq_) const {
;     ...
;             for (int bj = 0; bj < 2; ++bj) {
;                 f32x4 v0 = acc[ai][bj][m][0], v1 = acc[ai][bj][m][1];
;                 if (rotl) {
;                     f32x4 w0, w1;
;                     w0[0] = v0[0] * cs0[0] - v0[1] * cs0[1]; w0[1] = v0[1] * cs0[0] + v0[0] * cs0[1];
;                     w0[2] = v0[2] * cs1[0] - v0[3] * cs1[1]; w0[3] = v0[3] * cs1[0] + v0[2] * cs1[1];
;                     w1[0] = v1[0] * cs2[0] - v1[1] * cs2[1]; w1[1] = v1[1] * cs2[0] + v1[0] * cs2[1];
;                     w1[2] = v1[2] * cs3[0] - v1[3] * cs3[1]; w1[3] = v1[3] * cs3[0] + v1[2] * cs3[1];
;                     v0 = w0; v1 = w1;
;                 }
;                 u32x4 w; w.x = cvt_pk_bf16(v0[0], v0[1]); w.y = cvt_pk_bf16(v0[2], v0[3]); w.z = cvt_pk_bf16(v1[0], v1[1]); w.w = cvt_pk_bf16(v1[2], v1[3]);
;                 *(u32x4*)(rowp + bj * hstep) = w;
.LBB0_248:
	s_nop 1
	v_pk_mul_f32 v[22:23], v[14:15], v[62:63] op_sel:[1,1] op_sel_hi:[0,1]
	v_pk_mul_f32 v[20:21], v[14:15], v[62:63]
	v_pk_fma_f32 v[14:15], v[14:15], v[62:63], v[22:23] op_sel_hi:[1,0,1]
	v_pk_mul_f32 v[28:29], v[10:11], v[58:59] op_sel:[1,1] op_sel_hi:[0,1]
	v_mul_f32_e32 v14, v17, v65
	v_pk_fma_f32 v[24:25], v[16:17], v[64:65], v[14:15] op_sel_hi:[1,1,0] neg_lo:[0,0,1] neg_hi:[0,0,1]
	v_mul_f32_e32 v14, v16, v65
	v_pk_fma_f32 v[26:27], v[16:17], v[64:65], v[14:15] op_sel:[1,0,0] op_sel_hi:[0,1,0]
	v_pk_mul_f32 v[16:17], v[10:11], v[58:59]
	v_pk_fma_f32 v[10:11], v[10:11], v[58:59], v[28:29] op_sel_hi:[1,0,1]
	v_sub_f32_e32 v14, v20, v22
	v_mul_f32_e32 v10, v13, v61
	v_pk_fma_f32 v[30:31], v[12:13], v[60:61], v[10:11] op_sel_hi:[1,1,0] neg_lo:[0,0,1] neg_hi:[0,0,1]
	v_mul_f32_e32 v10, v12, v61
	v_pk_fma_f32 v[32:33], v[12:13], v[60:61], v[10:11] op_sel:[1,0,0] op_sel_hi:[0,1,0]
	v_sub_f32_e32 v10, v16, v28
	v_mov_b32_e32 v16, v24
	v_mov_b32_e32 v17, v26
	v_mov_b32_e32 v12, v30
	v_mov_b32_e32 v13, v32
.LBB0_249:
	s_or_b64 exec, exec, s[40:41]
	v_cvt_pk_bf16_f32 v14, v14, v15
	v_cvt_pk_bf16_f32 v15, v16, v17
	v_cvt_pk_bf16_f32 v16, v10, v11
	v_cvt_pk_bf16_f32 v17, v12, v13
	global_store_dwordx4 v[18:19], v[14:17], off
	s_and_saveexec_b64 s[40:41], s[38:39]
	s_cbranch_execz .LBB0_251
	s_nop 1
	v_pk_mul_f32 v[12:13], v[6:7], v[62:63] op_sel:[1,1] op_sel_hi:[0,1]
	v_pk_mul_f32 v[10:11], v[6:7], v[62:63]
	v_pk_fma_f32 v[6:7], v[6:7], v[62:63], v[12:13] op_sel_hi:[1,0,1]
	v_pk_mul_f32 v[20:21], v[2:3], v[58:59] op_sel:[1,1] op_sel_hi:[0,1]
	v_mul_f32_e32 v6, v9, v65
	v_pk_fma_f32 v[14:15], v[8:9], v[64:65], v[6:7] op_sel_hi:[1,1,0] neg_lo:[0,0,1] neg_hi:[0,0,1]
	v_mul_f32_e32 v6, v8, v65
	v_pk_fma_f32 v[16:17], v[8:9], v[64:65], v[6:7] op_sel:[1,0,0] op_sel_hi:[0,1,0]
	v_pk_mul_f32 v[8:9], v[2:3], v[58:59]
	v_pk_fma_f32 v[2:3], v[2:3], v[58:59], v[20:21] op_sel_hi:[1,0,1]
	v_sub_f32_e32 v6, v10, v12
	v_mul_f32_e32 v2, v5, v61
	v_pk_fma_f32 v[22:23], v[4:5], v[60:61], v[2:3] op_sel_hi:[1,1,0] neg_lo:[0,0,1] neg_hi:[0,0,1]
	v_mul_f32_e32 v2, v4, v61
	v_pk_fma_f32 v[24:25], v[4:5], v[60:61], v[2:3] op_sel:[1,0,0] op_sel_hi:[0,1,0]
	v_sub_f32_e32 v2, v8, v20
	v_mov_b32_e32 v8, v14
	v_mov_b32_e32 v9, v16
	v_mov_b32_e32 v4, v22
	v_mov_b32_e32 v5, v24
